# all validated edits combined: v65 (rmsnorm pipelining, gating load widening, DPP sums) plus proj mixer weight prefetch
# speedup vs baseline: 1.0053x; 1.0053x over previous
; #define LAS __attribute__((address_space(3)))
; #define OPQV(x) asm volatile("" : "+v"(x))
; DEV void sgu_item(LAS unsigned char* lds, const bf16_t* P, const bf16_t* VN, const float* sgu_w, const float* sgu_b, bf16_t* OC, int item) {
;     int tid = threadIdx.x; OPQV(tid); const int lane = tid & 63, wv = tid >> 6, fr = lane & 15, g4 = lane >> 4;
;     LAS bf16_t* VT = (LAS bf16_t*)lds;
;     const int g = item & 7, ch = (item >> 3) & 15, b = item >> 7;
;     const size_t tok0 = (size_t)b * S_ + ch * 128;
;     const int t = wv * 16 + fr;
;     const size_t tok = tok0 + t;
;     u32x4 vin[4];
; #pragma unroll
;     for (int it = 0; it < 4; ++it) { const int idx = it * 512 + tid, s = idx >> 4, c8 = (idx & 15) * 8; vin[it] = *(const u32x4*)(VN + (tok0 + s) * 1024 + g * 128 + c8); }
;     const float* wrow = sgu_w + ((size_t)g * 128 + t) * 128;
;     f32x4 wa[4], wb[4];
; #pragma unroll
;     for (int ks = 0; ks < 4; ++ks) { wa[ks] = *(const f32x4*)(wrow + ks * 32 + g4 * 8); wb[ks] = *(const f32x4*)(wrow + ks * 32 + g4 * 8 + 4); }
;     u32x2 uu[8];
; #pragma unroll
;     for (int n = 0; n < 8; ++n) uu[n] = *(const u32x2*)(P + tok * NP + COL_U + g * 128 + n * 16 + g4 * 4);
;     const float bias = sgu_b[g * 128 + t];
; #pragma unroll
;     for (int it = 0; it < 4; ++it) { const int idx = it * 512 + tid, s = idx >> 4, c8 = (idx & 15) * 8;
; #pragma unroll
;         for (int j = 0; j < 4; ++j) { VT[(c8 + 2 * j) * 136 + s] = (bf16_t)(vin[it][j] & 0xffffu); VT[(c8 + 2 * j + 1) * 136 + s] = (bf16_t)(vin[it][j] >> 16); } }
;     __syncthreads();
; DEV void phase_mix(LAS unsigned char* lds, const bf16_t* P, const bf16_t* QB, const bf16_t* KV, const bf16_t* KC, const bf16_t* VC, const float* rel_bias, bf16_t* OB,
;                    const bf16_t* VN, const float* sgu_w, const float* sgu_b, bf16_t* OC, int* ctr) {
;     ...
;     for (;;) {
;         if (tid == 0) *(LAS int*)(lds + AT_NEXT) = atomicAdd(ctr, 1);
;         __syncthreads();
;         const int i = *(const LAS int*)(lds + AT_NEXT);
;         __syncthreads();
;         if (i >= 2048) break;
;         if (i < 1024) attn_item(lds, P, QB, KV, KC, VC, rel_bias, OB, (i & 31) >> 2, i & 3, 31 - (i >> 5));
;         else sgu_item(lds, P, VN, sgu_w, sgu_b, OC, i - 1024);
.LBB0_164:
	s_or_b64 exec, exec, s[4:5]
	v_mov_b32_e32 v0, s95
	s_waitcnt lgkmcnt(0)
	s_barrier
	ds_read_b32 v0, v0
	s_movk_i32 s4, 0x7ff
	s_waitcnt lgkmcnt(0)
	s_barrier
	v_cmp_lt_i32_e32 vcc, s4, v0
	v_readfirstlane_b32 s43, v0
	s_mov_b64 s[4:5], -1
	s_cbranch_vccnz .LBB0_159
	s_cmpk_gt_i32 s43, 0x3ff
	s_cbranch_scc0 .LBB0_167
	s_add_i32 s4, s43, 0xfffffc00
	s_lshl_b32 s5, s4, 4
	s_lshl_b32 s4, s4, 7
	v_mov_b32_e32 v8, v210
	s_and_b32 s6, s4, 0x380
	s_and_b32 s36, s5, 0x3f80
	v_lshlrev_b32_e32 v0, 3, v8
	s_lshl_b32 s4, s6, 1
	v_and_b32_e32 v9, 0x78, v0
	s_add_u32 s44, s34, s4
	v_ashrrev_i32_e32 v4, 4, v8
	s_addc_u32 s45, s35, 0
	v_lshlrev_b32_e32 v0, 1, v9
	v_ashrrev_i32_e32 v5, 31, v4
	v_lshl_add_u64 v[2:3], s[44:45], 0, v[0:1]
	v_lshl_add_u64 v[6:7], v[4:5], 0, s[36:37]
	v_add_u32_e32 v0, 0x200, v8
	v_lshlrev_b64 v[6:7], 11, v[6:7]
	v_ashrrev_i32_e32 v70, 4, v0
	v_lshl_add_u64 v[6:7], v[2:3], 0, v[6:7]
	v_ashrrev_i32_e32 v71, 31, v70
	global_load_dwordx4 v[30:33], v[6:7], off
	v_lshl_add_u64 v[6:7], v[70:71], 0, s[36:37]
	v_add_u32_e32 v0, 0x400, v8
	v_lshlrev_b64 v[6:7], 11, v[6:7]
	v_ashrrev_i32_e32 v72, 4, v0
	v_lshl_add_u64 v[6:7], v[2:3], 0, v[6:7]
	v_ashrrev_i32_e32 v73, 31, v72
	global_load_dwordx4 v[34:37], v[6:7], off
	v_lshl_add_u64 v[6:7], v[72:73], 0, s[36:37]
	v_add_u32_e32 v0, 0x600, v8
	v_lshlrev_b64 v[6:7], 11, v[6:7]
	v_ashrrev_i32_e32 v74, 4, v0
	v_lshl_add_u64 v[6:7], v[2:3], 0, v[6:7]
	v_ashrrev_i32_e32 v75, 31, v74
	global_load_dwordx4 v[38:41], v[6:7], off
	v_lshl_add_u64 v[6:7], v[74:75], 0, s[36:37]
	v_ashrrev_i32_e32 v0, 2, v8
	v_lshlrev_b64 v[6:7], 11, v[6:7]
	s_waitcnt vmcnt(11)
	v_bfi_b32 v28, -16, v0, v8
	v_lshl_add_u64 v[2:3], v[2:3], 0, v[6:7]
	v_ashrrev_i32_e32 v29, 31, v28
	s_mov_b32 s7, s37
	global_load_dwordx4 v[42:45], v[2:3], off
	v_lshl_add_u64 v[2:3], v[28:29], 0, s[6:7]
	v_bfe_u32 v0, v8, 4, 2
	v_lshlrev_b64 v[2:3], 9, v[2:3]
	v_lshl_add_u64 v[2:3], s[80:81], 0, v[2:3]
	v_lshlrev_b32_e32 v6, 5, v0
	v_mov_b32_e32 v7, v1
	v_lshl_add_u64 v[6:7], v[2:3], 0, v[6:7]
	global_load_dwordx4 v[46:49], v[6:7], off
	global_load_dwordx4 v[50:53], v[6:7], off offset:16
	v_mov_b64_e32 v[2:3], s[76:77]
	v_and_b32_e32 v82, 15, v8
	v_add_u32_e32 v8, s6, v28
	s_movk_i32 s6, 0x110
	v_lshl_add_u64 v[24:25], v[28:29], 0, s[36:37]
	s_mov_b32 s5, s37
	v_mad_u32_u24 v71, v9, s6, 0
	v_ashrrev_i32_e32 v9, 31, v8
	v_mad_i64_i32 v[2:3], s[6:7], v24, s59, v[2:3]
	v_lshl_add_u32 v73, v4, 1, v71
	v_lshlrev_b32_e32 v0, 3, v0
	v_lshl_add_u64 v[4:5], v[8:9], 2, s[82:83]
	v_lshl_add_u64 v[2:3], v[2:3], 0, s[4:5]
	global_load_dword v29, v[4:5], off
	v_lshl_add_u64 v[10:11], v[2:3], 0, v[0:1]
	global_load_dwordx4 v[54:57], v[6:7], off offset:144
	global_load_dwordx4 v[58:61], v[6:7], off offset:128
	global_load_dwordx4 v[62:65], v[6:7], off offset:272
	global_load_dwordx4 v[66:69], v[6:7], off offset:256
	global_load_dwordx4 v[2:5], v[6:7], off offset:400
	s_nop 0
	global_load_dwordx4 v[6:9], v[6:7], off offset:384
	s_mov_b64 s[6:7], 0x2c00
	s_movk_i32 s5, 0x2000
	v_lshl_add_u64 v[76:77], v[10:11], 0, s[6:7]
	v_and_b32_e32 v120, 16, v213
	v_lshrrev_b32_e32 v121, 1, v120
	v_add_u32_e32 v120, v120, v121
	v_mov_b32_e32 v121, 0
	v_lshl_add_u64 v[138:139], v[76:77], 0, v[120:121]
	v_add_co_u32_e32 v10, vcc, s5, v10
	v_or_b32_e32 v90, 32, v0
	s_nop 0
	v_addc_co_u32_e32 v11, vcc, 0, v11, vcc
	global_load_dwordx4 v[122:125], v[138:139], off
	global_load_dwordx4 v[126:129], v[138:139], off offset:64
	global_load_dwordx4 v[130:133], v[138:139], off offset:128
	global_load_dwordx4 v[134:137], v[138:139], off offset:192
	s_nop 0
	v_cmp_le_i32_e32 vcc, v0, v28
	v_or_b32_e32 v91, 33, v0
	s_movk_i32 s5, 0x88
	v_mad_u32_u24 v83, v82, s5, v227
	v_mov_b32_e32 v252, 0x1100
	v_mad_u32_u24 v84, v82, s5, v252
	v_mad_u32_u24 v85, v82, s5, v216
	v_mad_u32_u24 v86, v82, s5, v217
	v_mad_u32_u24 v87, v82, s5, v218
	s_waitcnt vmcnt(16)
	ds_write_b16 v73, v30
	ds_write_b16_d16_hi v73, v30 offset:272
	ds_write_b16 v73, v31 offset:544
	ds_write_b16_d16_hi v73, v31 offset:816
	ds_write_b16 v73, v32 offset:1088
	ds_write_b16_d16_hi v73, v32 offset:1360
	ds_write_b16 v73, v33 offset:1632
	ds_write_b16_d16_hi v73, v33 offset:1904
	v_lshl_add_u32 v30, v70, 1, v71
	s_waitcnt vmcnt(15)
	ds_write_b16 v30, v34
	ds_write_b16_d16_hi v30, v34 offset:272
	ds_write_b16 v30, v35 offset:544
	ds_write_b16_d16_hi v30, v35 offset:816
	ds_write_b16 v30, v36 offset:1088
	ds_write_b16_d16_hi v30, v36 offset:1360
	ds_write_b16 v30, v37 offset:1632
	ds_write_b16_d16_hi v30, v37 offset:1904
	v_lshl_add_u32 v30, v72, 1, v71
	s_waitcnt vmcnt(14)
	ds_write_b16 v30, v38
	ds_write_b16_d16_hi v30, v38 offset:272
	ds_write_b16 v30, v39 offset:544
	ds_write_b16_d16_hi v30, v39 offset:816
	ds_write_b16 v30, v40 offset:1088
	ds_write_b16_d16_hi v30, v40 offset:1360
	ds_write_b16 v30, v41 offset:1632
	ds_write_b16_d16_hi v30, v41 offset:1904
	v_lshl_add_u32 v30, v74, 1, v71
	s_waitcnt vmcnt(13)
	ds_write_b16 v30, v42
	ds_write_b16_d16_hi v30, v42 offset:272
	ds_write_b16 v30, v43 offset:544
	ds_write_b16_d16_hi v30, v43 offset:816
	ds_write_b16 v30, v44 offset:1088
	ds_write_b16_d16_hi v30, v44 offset:1360
	ds_write_b16 v30, v45 offset:1632
	ds_write_b16_d16_hi v30, v45 offset:1904
	v_or_b32_e32 v32, 2, v0
	v_or_b32_e32 v33, 3, v0
	v_or_b32_e32 v34, 4, v0
	v_or_b32_e32 v35, 5, v0
	v_or_b32_e32 v36, 6, v0
	v_or_b32_e32 v37, 7, v0
	s_waitcnt vmcnt(12) lgkmcnt(0)
	v_cndmask_b32_e32 v30, 0, v46, vcc
	v_cmp_lt_i32_e32 vcc, v0, v28
	s_barrier
; #define LAS __attribute__((address_space(3)))
; DEV u32x4 pack8(const float (&f)[8]) { u32x4 w; w.x = cvt_pk_bf16(f[0], f[1]); w.y = cvt_pk_bf16(f[2], f[3]); w.z = cvt_pk_bf16(f[4], f[5]); w.w = cvt_pk_bf16(f[6], f[7]); return w; }
; DEV void sgu_item(LAS unsigned char* lds, const bf16_t* P, const bf16_t* VN, const float* sgu_w, const float* sgu_b, bf16_t* OC, int item) {
;     ...
; #pragma unroll
;     for (int ks = 0; ks < 4; ++ks) { const int s0 = ks * 32 + g4 * 8;
;         float wf[8] = {wa[ks][0], wa[ks][1], wa[ks][2], wa[ks][3], wb[ks][0], wb[ks][1], wb[ks][2], wb[ks][3]};
; #pragma unroll
;         for (int j = 0; j < 8; ++j) if (s0 + j > t) wf[j] = 0.f;
;         const bf16x8 wfr = as_bf16x8(pack8(wf));
; #pragma unroll
;         for (int n = 0; n < 8; ++n) { const bf16x8 vf = *(const LAS bf16x8*)(lds + ((n * 16 + fr) * 136 + s0) * 2);
;             acc[n] = __builtin_amdgcn_mfma_f32_16x16x32_bf16(vf, wfr, acc[n], 0, 0, 0); } }
	s_nop 0
	v_cndmask_b32_e32 v31, 0, v47, vcc
	v_cmp_le_i32_e32 vcc, v32, v28
	v_cvt_pk_bf16_f32 v30, v30, v31
	v_mad_u32_u24 v88, v82, s5, v219
	v_mad_u32_u24 v89, v82, s5, v220
	v_cndmask_b32_e32 v32, 0, v48, vcc
	v_cmp_le_i32_e32 vcc, v33, v28
	v_add_u32_e32 v38, v83, v0
	v_add_u32_e32 v42, v84, v0
	v_cndmask_b32_e32 v33, 0, v49, vcc
	v_cmp_le_i32_e32 vcc, v34, v28
	v_cvt_pk_bf16_f32 v31, v32, v33
	v_add_u32_e32 v46, v85, v0
	v_add_u32_e32 v70, v87, v0
	s_waitcnt vmcnt(11)
	v_cndmask_b32_e32 v34, 0, v50, vcc
	v_cmp_le_i32_e32 vcc, v35, v28
	v_add_u32_e32 v50, v86, v0
	v_add_u32_e32 v74, v88, v0
	v_cndmask_b32_e32 v35, 0, v51, vcc
	v_cmp_le_i32_e32 vcc, v36, v28
	v_cvt_pk_bf16_f32 v32, v34, v35
	v_mad_u32_u24 v34, v82, s5, v0
	v_lshl_add_u32 v34, v34, 1, 0
	v_cndmask_b32_e32 v36, 0, v52, vcc
	v_cmp_le_i32_e32 vcc, v37, v28
	v_add_u32_e32 v78, v89, v0
	v_lshl_add_u32 v38, v38, 1, 0
	v_cndmask_b32_e32 v37, 0, v53, vcc
	v_cmp_le_i32_e32 vcc, v90, v28
	v_cvt_pk_bf16_f32 v33, v36, v37
	ds_read_b128 v[34:37], v34
	ds_read_b128 v[38:41], v38
	s_waitcnt vmcnt(8)
	v_cndmask_b32_e32 v58, 0, v58, vcc
	v_cmp_le_i32_e32 vcc, v91, v28
	v_or_b32_e32 v91, 34, v0
	v_lshl_add_u32 v42, v42, 1, 0
	v_cndmask_b32_e32 v59, 0, v59, vcc
	v_cmp_le_i32_e32 vcc, v91, v28
	v_or_b32_e32 v91, 35, v0
	v_lshl_add_u32 v46, v46, 1, 0
	v_cndmask_b32_e32 v60, 0, v60, vcc
	v_cmp_le_i32_e32 vcc, v91, v28
	v_or_b32_e32 v91, 36, v0
	v_lshl_add_u32 v50, v50, 1, 0
	v_cndmask_b32_e32 v61, 0, v61, vcc
	v_cmp_le_i32_e32 vcc, v91, v28
	v_lshl_add_u32 v70, v70, 1, 0
	v_lshl_add_u32 v74, v74, 1, 0
	v_cndmask_b32_e32 v91, 0, v54, vcc
	v_or_b32_e32 v54, 37, v0
	v_cmp_le_i32_e32 vcc, v54, v28
	v_or_b32_e32 v54, 38, v0
	v_lshl_add_u32 v78, v78, 1, 0
	v_cndmask_b32_e32 v92, 0, v55, vcc
	v_cmp_le_i32_e32 vcc, v54, v28
	v_or_b32_e32 v54, 39, v0
	ds_read_b128 v[42:45], v42
	ds_read_b128 v[46:49], v46
	ds_read_b128 v[50:53], v50
	ds_read_b128 v[70:73], v70
	ds_read_b128 v[74:77], v74
	ds_read_b128 v[78:81], v78
	v_cndmask_b32_e32 v93, 0, v56, vcc
	v_cmp_le_i32_e32 vcc, v54, v28
	v_cvt_pk_bf16_f32 v54, v58, v59
	v_mad_u32_u24 v58, v82, s5, v90
	v_lshl_add_u32 v58, v58, 1, 0
	v_cndmask_b32_e32 v57, 0, v57, vcc
	v_cvt_pk_bf16_f32 v55, v60, v61
	v_cvt_pk_bf16_f32 v56, v91, v92
	v_cvt_pk_bf16_f32 v57, v93, v57
	ds_read_b128 v[58:61], v58
	s_waitcnt lgkmcnt(8)
	v_mfma_f32_16x16x32_bf16 v[34:37], v[34:37], v[30:33], 0
	v_lshlrev_b64 v[24:25], 11, v[24:25]
	v_lshl_add_u64 v[24:25], s[88:89], 0, v[24:25]
	s_waitcnt lgkmcnt(7)
	v_mfma_f32_16x16x32_bf16 v[38:41], v[38:41], v[30:33], 0
	s_waitcnt lgkmcnt(6)
	v_mfma_f32_16x16x32_bf16 v[42:45], v[42:45], v[30:33], 0
	s_waitcnt lgkmcnt(5)
	v_mfma_f32_16x16x32_bf16 v[46:49], v[46:49], v[30:33], 0
	s_waitcnt lgkmcnt(4)
	v_mfma_f32_16x16x32_bf16 v[50:53], v[50:53], v[30:33], 0
	s_waitcnt lgkmcnt(3)
	v_mfma_f32_16x16x32_bf16 v[70:73], v[70:73], v[30:33], 0
	s_waitcnt lgkmcnt(2)
	v_mfma_f32_16x16x32_bf16 v[74:77], v[74:77], v[30:33], 0
	s_waitcnt lgkmcnt(1)
	v_mfma_f32_16x16x32_bf16 v[30:33], v[78:81], v[30:33], 0
	v_add_u32_e32 v78, v90, v83
	v_lshl_add_u32 v78, v78, 1, 0
	ds_read_b128 v[78:81], v78
	s_waitcnt lgkmcnt(1)
	v_mfma_f32_16x16x32_bf16 v[34:37], v[58:61], v[54:57], v[34:37]
	v_add_u32_e32 v58, v90, v84
	v_lshl_add_u32 v58, v58, 1, 0
	ds_read_b128 v[58:61], v58
	s_waitcnt lgkmcnt(1)
	v_mfma_f32_16x16x32_bf16 v[38:41], v[78:81], v[54:57], v[38:41]
	v_add_u32_e32 v78, v90, v85
	v_lshl_add_u32 v78, v78, 1, 0
	ds_read_b128 v[78:81], v78
	s_waitcnt lgkmcnt(1)
	v_mfma_f32_16x16x32_bf16 v[42:45], v[58:61], v[54:57], v[42:45]
	v_add_u32_e32 v58, v90, v86
	v_lshl_add_u32 v58, v58, 1, 0
	ds_read_b128 v[58:61], v58
	s_waitcnt lgkmcnt(1)
	v_mfma_f32_16x16x32_bf16 v[46:49], v[78:81], v[54:57], v[46:49]
	v_add_u32_e32 v78, v90, v87
	v_lshl_add_u32 v78, v78, 1, 0
	ds_read_b128 v[78:81], v78
	s_waitcnt lgkmcnt(1)
	v_mfma_f32_16x16x32_bf16 v[50:53], v[58:61], v[54:57], v[50:53]
	v_add_u32_e32 v58, v90, v88
	v_lshl_add_u32 v58, v58, 1, 0
	ds_read_b128 v[58:61], v58
	s_waitcnt lgkmcnt(1)
	v_mfma_f32_16x16x32_bf16 v[70:73], v[78:81], v[54:57], v[70:73]
	v_add_u32_e32 v78, v90, v89
	v_lshl_add_u32 v78, v78, 1, 0
	ds_read_b128 v[78:81], v78
	s_waitcnt lgkmcnt(1)
	v_mfma_f32_16x16x32_bf16 v[58:61], v[58:61], v[54:57], v[74:77]
	s_nop 2
	v_or_b32_e32 v74, 64, v0
	v_cmp_le_i32_e32 vcc, v74, v28
	v_or_b32_e32 v75, 0x41, v0
	s_waitcnt lgkmcnt(0)
	v_mfma_f32_16x16x32_bf16 v[30:33], v[78:81], v[54:57], v[30:33]
	s_waitcnt vmcnt(6)
	v_cndmask_b32_e32 v66, 0, v66, vcc
	v_cmp_le_i32_e32 vcc, v75, v28
	v_or_b32_e32 v75, 0x42, v0
	v_add_u32_e32 v54, v74, v83
	v_cndmask_b32_e32 v67, 0, v67, vcc
	v_cmp_le_i32_e32 vcc, v75, v28
	v_or_b32_e32 v75, 0x43, v0
	v_lshl_add_u32 v54, v54, 1, 0
	v_cndmask_b32_e32 v68, 0, v68, vcc
	v_cmp_le_i32_e32 vcc, v75, v28
	v_or_b32_e32 v75, 0x44, v0
	s_nop 0
	v_cndmask_b32_e32 v69, 0, v69, vcc
	v_cmp_le_i32_e32 vcc, v75, v28
	s_nop 1
	v_cndmask_b32_e32 v75, 0, v62, vcc
	v_or_b32_e32 v62, 0x45, v0
	v_cmp_le_i32_e32 vcc, v62, v28
	v_or_b32_e32 v62, 0x46, v0
	s_nop 0
	v_cndmask_b32_e32 v76, 0, v63, vcc
	v_cmp_le_i32_e32 vcc, v62, v28
	v_or_b32_e32 v62, 0x47, v0
	s_nop 0
	v_cndmask_b32_e32 v77, 0, v64, vcc
	v_cmp_le_i32_e32 vcc, v62, v28
	v_cvt_pk_bf16_f32 v62, v66, v67
	v_mad_u32_u24 v66, v82, s5, v74
	v_lshl_add_u32 v66, v66, 1, 0
	v_cndmask_b32_e32 v65, 0, v65, vcc
	v_cvt_pk_bf16_f32 v63, v68, v69
	v_cvt_pk_bf16_f32 v64, v75, v76
	v_cvt_pk_bf16_f32 v65, v77, v65
	ds_read_b128 v[66:69], v66
	ds_read_b128 v[54:57], v54
	s_waitcnt lgkmcnt(1)
	v_mfma_f32_16x16x32_bf16 v[34:37], v[66:69], v[62:65], v[34:37]
	v_add_u32_e32 v66, v74, v84
	v_lshl_add_u32 v66, v66, 1, 0
	ds_read_b128 v[66:69], v66
	s_waitcnt lgkmcnt(1)
; #define LAS __attribute__((address_space(3)))
; DEV float bflo(unsigned u) { return __uint_as_float(u << 16); }
; DEV float bfhi(unsigned u) { return __uint_as_float(u & 0xffff0000u); }
; DEV unsigned cvt_pk_bf16(float lo, float hi) { unsigned r; asm volatile("v_cvt_pk_bf16_f32 %0, %1, %2" : "=v"(r) : "v"(lo), "v"(hi)); return r; }
; DEV u32x4 pack8(const float (&f)[8]) { u32x4 w; w.x = cvt_pk_bf16(f[0], f[1]); w.y = cvt_pk_bf16(f[2], f[3]); w.z = cvt_pk_bf16(f[4], f[5]); w.w = cvt_pk_bf16(f[6], f[7]); return w; }
; DEV void sgu_item(LAS unsigned char* lds, const bf16_t* P, const bf16_t* VN, const float* sgu_w, const float* sgu_b, bf16_t* OC, int item) {
;     ...
;     for (int ks = 0; ks < 4; ++ks) { const int s0 = ks * 32 + g4 * 8;
;         float wf[8] = {wa[ks][0], wa[ks][1], wa[ks][2], wa[ks][3], wb[ks][0], wb[ks][1], wb[ks][2], wb[ks][3]};
; #pragma unroll
;         for (int j = 0; j < 8; ++j) if (s0 + j > t) wf[j] = 0.f;
;         const bf16x8 wfr = as_bf16x8(pack8(wf));
; #pragma unroll
;         for (int n = 0; n < 8; ++n) { const bf16x8 vf = *(const LAS bf16x8*)(lds + ((n * 16 + fr) * 136 + s0) * 2);
;             acc[n] = __builtin_amdgcn_mfma_f32_16x16x32_bf16(vf, wfr, acc[n], 0, 0, 0); } }
; #pragma unroll
;     for (int n = 0; n < 8; ++n) { const int c = g * 128 + n * 16 + g4 * 4;
;         u32x2 w; w.x = cvt_pk_bf16(bflo(uu[n].x) * (acc[n][0] + bias), bfhi(uu[n].x) * (acc[n][1] + bias)); w.y = cvt_pk_bf16(bflo(uu[n].y) * (acc[n][2] + bias), bfhi(uu[n].y) * (acc[n][3] + bias));
;         *(u32x2*)(OC + tok * 1024 + c) = w; }
	v_mfma_f32_16x16x32_bf16 v[38:41], v[54:57], v[62:65], v[38:41]
	v_add_u32_e32 v54, v74, v85
	v_lshl_add_u32 v54, v54, 1, 0
	ds_read_b128 v[54:57], v54
	s_waitcnt lgkmcnt(1)
	v_mfma_f32_16x16x32_bf16 v[42:45], v[66:69], v[62:65], v[42:45]
	v_add_u32_e32 v66, v74, v86
	v_lshl_add_u32 v66, v66, 1, 0
	ds_read_b128 v[66:69], v66
	s_waitcnt lgkmcnt(1)
	v_mfma_f32_16x16x32_bf16 v[46:49], v[54:57], v[62:65], v[46:49]
	v_add_u32_e32 v54, v74, v87
	v_lshl_add_u32 v54, v54, 1, 0
	ds_read_b128 v[54:57], v54
	s_waitcnt lgkmcnt(1)
	v_mfma_f32_16x16x32_bf16 v[50:53], v[66:69], v[62:65], v[50:53]
	v_add_u32_e32 v66, v74, v88
	v_lshl_add_u32 v66, v66, 1, 0
	ds_read_b128 v[66:69], v66
	s_waitcnt lgkmcnt(1)
	v_mfma_f32_16x16x32_bf16 v[54:57], v[54:57], v[62:65], v[70:73]
	s_nop 2
	v_add_u32_e32 v70, v74, v89
	v_lshl_add_u32 v70, v70, 1, 0
	ds_read_b128 v[70:73], v70
	s_waitcnt lgkmcnt(1)
	v_mfma_f32_16x16x32_bf16 v[58:61], v[66:69], v[62:65], v[58:61]
	v_or_b32_e32 v66, 0x60, v0
	v_cmp_le_i32_e32 vcc, v66, v28
	v_or_b32_e32 v67, 0x61, v0
	s_waitcnt lgkmcnt(0)
	v_mfma_f32_16x16x32_bf16 v[30:33], v[70:73], v[62:65], v[30:33]
	s_waitcnt vmcnt(4)
	v_cndmask_b32_e32 v6, 0, v6, vcc
	v_cmp_le_i32_e32 vcc, v67, v28
	v_or_b32_e32 v67, 0x62, v0
	s_nop 0
	v_cndmask_b32_e32 v7, 0, v7, vcc
	v_cmp_le_i32_e32 vcc, v67, v28
	v_or_b32_e32 v67, 0x63, v0
	s_nop 0
	v_cndmask_b32_e32 v8, 0, v8, vcc
	v_cmp_le_i32_e32 vcc, v67, v28
	v_or_b32_e32 v67, 0x64, v0
	s_nop 0
	v_cndmask_b32_e32 v9, 0, v9, vcc
	v_cmp_le_i32_e32 vcc, v67, v28
	s_nop 1
	v_cndmask_b32_e32 v67, 0, v2, vcc
	v_or_b32_e32 v2, 0x65, v0
	v_cmp_le_i32_e32 vcc, v2, v28
	v_or_b32_e32 v2, 0x66, v0
	s_nop 0
	v_cndmask_b32_e32 v68, 0, v3, vcc
	v_cmp_le_i32_e32 vcc, v2, v28
	v_or_b32_e32 v2, 0x67, v0
	v_or_b32_e32 v0, s4, v0
	v_cndmask_b32_e32 v69, 0, v4, vcc
	v_cmp_le_i32_e32 vcc, v2, v28
	v_cvt_pk_bf16_f32 v2, v6, v7
	v_mad_u32_u24 v6, v82, s5, v66
	v_lshl_add_u32 v6, v6, 1, 0
	v_cndmask_b32_e32 v5, 0, v5, vcc
	v_cvt_pk_bf16_f32 v3, v8, v9
	v_cvt_pk_bf16_f32 v4, v67, v68
	v_cvt_pk_bf16_f32 v5, v69, v5
	ds_read_b128 v[6:9], v6
	v_add_u32_e32 v28, v66, v83
	v_lshl_add_u32 v28, v28, 1, 0
	ds_read_b128 v[62:65], v28
	v_add_u32_e32 v28, v66, v84
	v_lshl_add_u32 v28, v28, 1, 0
	s_waitcnt lgkmcnt(1)
	v_mfma_f32_16x16x32_bf16 v[6:9], v[6:9], v[2:5], v[34:37]
	s_nop 2
	ds_read_b128 v[34:37], v28
	v_add_u32_e32 v28, v66, v85
	v_lshl_add_u32 v28, v28, 1, 0
	s_waitcnt lgkmcnt(1)
	v_mfma_f32_16x16x32_bf16 v[38:41], v[62:65], v[2:5], v[38:41]
	ds_read_b128 v[62:65], v28
	v_add_u32_e32 v28, v66, v86
	v_lshl_add_u32 v28, v28, 1, 0
	s_waitcnt lgkmcnt(1)
	v_mfma_f32_16x16x32_bf16 v[34:37], v[34:37], v[2:5], v[42:45]
	v_add_f32_e32 v6, v29, v6
	s_nop 1
	ds_read_b128 v[42:45], v28
	v_add_u32_e32 v28, v66, v87
	v_lshl_add_u32 v28, v28, 1, 0
	s_waitcnt lgkmcnt(1)
	v_mfma_f32_16x16x32_bf16 v[46:49], v[62:65], v[2:5], v[46:49]
	ds_read_b128 v[62:65], v28
	v_add_u32_e32 v28, v66, v88
	v_lshl_add_u32 v28, v28, 1, 0
	s_waitcnt lgkmcnt(1)
	v_mfma_f32_16x16x32_bf16 v[42:45], v[42:45], v[2:5], v[50:53]
	v_add_f32_e32 v7, v29, v7
	s_nop 1
	ds_read_b128 v[50:53], v28
	v_add_u32_e32 v28, v66, v89
	v_lshl_add_u32 v28, v28, 1, 0
	s_waitcnt lgkmcnt(1)
	v_mfma_f32_16x16x32_bf16 v[54:57], v[62:65], v[2:5], v[54:57]
	ds_read_b128 v[62:65], v28
	s_waitcnt vmcnt(3)
	v_permlane16_swap_b32_e32 v122, v124
	v_permlane16_swap_b32_e32 v123, v125
	v_lshlrev_b32_e32 v28, 16, v122
	v_and_b32_e32 v122, 0xffff0000, v122
	v_mul_f32_e32 v6, v6, v28
	v_mul_f32_e32 v7, v7, v122
	v_cvt_pk_bf16_f32 v104, v6, v7
	v_lshlrev_b32_e32 v7, 16, v123
	v_add_f32_e32 v8, v29, v8
	v_mul_f32_e32 v7, v8, v7
	v_and_b32_e32 v8, 0xffff0000, v123
	v_add_f32_e32 v9, v29, v9
	v_mul_f32_e32 v8, v9, v8
	v_cvt_pk_bf16_f32 v105, v7, v8
	v_lshl_add_u64 v[8:9], v[24:25], 0, v[0:1]
	v_and_b32_e32 v120, 16, v213
	v_lshrrev_b32_e32 v121, 1, v120
	v_add_u32_e32 v120, v120, v121
	v_add_co_u32_e32 v8, vcc, v8, v120
	s_nop 1
	v_addc_co_u32_e32 v9, vcc, 0, v9, vcc
	v_lshlrev_b32_e32 v0, 16, v124
	v_add_f32_e32 v6, v29, v38
	v_mul_f32_e32 v0, v6, v0
	v_and_b32_e32 v6, 0xffff0000, v124
	v_add_f32_e32 v7, v29, v39
	v_mul_f32_e32 v6, v7, v6
	v_cvt_pk_bf16_f32 v106, v0, v6
	v_lshlrev_b32_e32 v0, 16, v125
	v_add_f32_e32 v7, v29, v40
	v_mul_f32_e32 v0, v7, v0
	v_and_b32_e32 v7, 0xffff0000, v125
	v_add_f32_e32 v124, v29, v41
	v_mul_f32_e32 v7, v124, v7
	v_cvt_pk_bf16_f32 v107, v0, v7
	s_nop 1
	v_permlane16_swap_b32_e32 v104, v106
	v_permlane16_swap_b32_e32 v105, v107
	global_store_dwordx4 v[8:9], v[104:107], off
	s_waitcnt vmcnt(3)
; DEV float bflo(unsigned u) { return __uint_as_float(u << 16); }
; DEV float bfhi(unsigned u) { return __uint_as_float(u & 0xffff0000u); }
; DEV unsigned cvt_pk_bf16(float lo, float hi) { unsigned r; asm volatile("v_cvt_pk_bf16_f32 %0, %1, %2" : "=v"(r) : "v"(lo), "v"(hi)); return r; }
; DEV void sgu_item(LAS unsigned char* lds, const bf16_t* P, const bf16_t* VN, const float* sgu_w, const float* sgu_b, bf16_t* OC, int item) {
;     ...
; #pragma unroll
;     for (int n = 0; n < 8; ++n) { const int c = g * 128 + n * 16 + g4 * 4;
;         u32x2 w; w.x = cvt_pk_bf16(bflo(uu[n].x) * (acc[n][0] + bias), bfhi(uu[n].x) * (acc[n][1] + bias)); w.y = cvt_pk_bf16(bflo(uu[n].y) * (acc[n][2] + bias), bfhi(uu[n].y) * (acc[n][3] + bias));
;         *(u32x2*)(OC + tok * 1024 + c) = w; }
;     __syncthreads();
	v_permlane16_swap_b32_e32 v126, v128
	v_permlane16_swap_b32_e32 v127, v129
	v_lshlrev_b32_e32 v0, 16, v126
	v_add_f32_e32 v6, v29, v34
	v_mul_f32_e32 v0, v6, v0
	v_and_b32_e32 v6, 0xffff0000, v126
	v_add_f32_e32 v7, v29, v35
	v_mul_f32_e32 v6, v7, v6
	v_cvt_pk_bf16_f32 v108, v0, v6
	v_lshlrev_b32_e32 v0, 16, v127
	v_add_f32_e32 v7, v29, v36
	v_mul_f32_e32 v0, v7, v0
	v_and_b32_e32 v7, 0xffff0000, v127
	v_add_f32_e32 v126, v29, v37
	v_mul_f32_e32 v7, v126, v7
	v_cvt_pk_bf16_f32 v109, v0, v7
	v_lshlrev_b32_e32 v0, 16, v128
	v_add_f32_e32 v6, v29, v46
	v_mul_f32_e32 v0, v6, v0
	v_and_b32_e32 v6, 0xffff0000, v128
	v_add_f32_e32 v7, v29, v47
	v_mul_f32_e32 v6, v7, v6
	v_cvt_pk_bf16_f32 v110, v0, v6
	v_lshlrev_b32_e32 v0, 16, v129
	v_add_f32_e32 v7, v29, v48
	v_mul_f32_e32 v0, v7, v0
	v_and_b32_e32 v7, 0xffff0000, v129
	v_add_f32_e32 v128, v29, v49
	v_mul_f32_e32 v7, v128, v7
	v_cvt_pk_bf16_f32 v111, v0, v7
	s_nop 1
	v_permlane16_swap_b32_e32 v108, v110
	v_permlane16_swap_b32_e32 v109, v111
	global_store_dwordx4 v[8:9], v[108:111], off offset:64
	s_waitcnt vmcnt(3)
	v_permlane16_swap_b32_e32 v130, v132
	v_permlane16_swap_b32_e32 v131, v133
	v_lshlrev_b32_e32 v0, 16, v130
	v_add_f32_e32 v6, v29, v42
	v_mul_f32_e32 v0, v6, v0
	v_and_b32_e32 v6, 0xffff0000, v130
	v_add_f32_e32 v7, v29, v43
	v_mul_f32_e32 v6, v7, v6
	v_cvt_pk_bf16_f32 v112, v0, v6
	v_lshlrev_b32_e32 v0, 16, v131
	v_add_f32_e32 v7, v29, v44
	v_mul_f32_e32 v0, v7, v0
	v_and_b32_e32 v7, 0xffff0000, v131
	v_add_f32_e32 v130, v29, v45
	v_mul_f32_e32 v7, v130, v7
	v_cvt_pk_bf16_f32 v113, v0, v7
	s_waitcnt vmcnt(4)
	v_lshlrev_b32_e32 v0, 16, v132
	v_add_f32_e32 v6, v29, v54
	v_mul_f32_e32 v0, v6, v0
	v_and_b32_e32 v6, 0xffff0000, v132
	v_add_f32_e32 v7, v29, v55
	s_waitcnt lgkmcnt(1)
	v_mfma_f32_16x16x32_bf16 v[50:53], v[50:53], v[2:5], v[58:61]
	v_mul_f32_e32 v6, v7, v6
	v_cvt_pk_bf16_f32 v114, v0, v6
	v_lshlrev_b32_e32 v0, 16, v133
	v_add_f32_e32 v7, v29, v56
	v_mul_f32_e32 v0, v7, v0
	v_and_b32_e32 v7, 0xffff0000, v133
	v_add_f32_e32 v132, v29, v57
	v_mul_f32_e32 v7, v132, v7
	v_cvt_pk_bf16_f32 v115, v0, v7
	s_nop 1
	v_permlane16_swap_b32_e32 v112, v114
	v_permlane16_swap_b32_e32 v113, v115
	global_store_dwordx4 v[8:9], v[112:115], off offset:128
	s_waitcnt vmcnt(3)
	v_permlane16_swap_b32_e32 v134, v136
	v_permlane16_swap_b32_e32 v135, v137
	v_lshlrev_b32_e32 v0, 16, v134
	v_add_f32_e32 v6, v29, v50
	v_mul_f32_e32 v0, v6, v0
	v_and_b32_e32 v6, 0xffff0000, v134
	v_add_f32_e32 v7, v29, v51
	s_waitcnt lgkmcnt(0)
	v_mfma_f32_16x16x32_bf16 v[2:5], v[62:65], v[2:5], v[30:33]
	v_mul_f32_e32 v6, v7, v6
	v_cvt_pk_bf16_f32 v116, v0, v6
	v_lshlrev_b32_e32 v0, 16, v135
	v_add_f32_e32 v7, v29, v52
	v_mul_f32_e32 v0, v7, v0
	v_and_b32_e32 v7, 0xffff0000, v135
	v_add_f32_e32 v134, v29, v53
	v_mul_f32_e32 v7, v134, v7
	v_cvt_pk_bf16_f32 v117, v0, v7
	s_waitcnt vmcnt(3)
	v_lshlrev_b32_e32 v0, 16, v136
	v_add_f32_e32 v2, v29, v2
	v_mul_f32_e32 v0, v2, v0
	v_and_b32_e32 v2, 0xffff0000, v136
	v_add_f32_e32 v3, v29, v3
	v_mul_f32_e32 v2, v3, v2
	v_cvt_pk_bf16_f32 v118, v0, v2
	v_lshlrev_b32_e32 v0, 16, v137
	v_add_f32_e32 v3, v29, v4
	v_mul_f32_e32 v0, v3, v0
	v_and_b32_e32 v3, 0xffff0000, v137
	v_add_f32_e32 v4, v29, v5
	v_mul_f32_e32 v3, v4, v3
	v_cvt_pk_bf16_f32 v119, v0, v3
	s_nop 1
	v_permlane16_swap_b32_e32 v116, v118
	v_permlane16_swap_b32_e32 v117, v119
	global_store_dwordx4 v[8:9], v[116:119], off offset:192
	s_barrier
	s_mov_b64 s[4:5], 0
